# tile-completion fused RMSNorm: whole-unit rows of the post-mixer rms phase are normalised at the end of the w_o GEMM phase by each token tile's last-column workgroup (tile counters); the rms phase kee
# baseline (speedup 1.0000x reference)
; #define LAS __attribute__((address_space(3)))
; __device__ __forceinline__ ArgP argp() { ArgP p = (ArgP)__builtin_amdgcn_kernarg_segment_ptr(); asm volatile("" : "+s"(p)); return p; }
; __global__ void __launch_bounds__(NTHREADS, 2) fwd_megakernel(Args a_) {
;     ArgP a = argp();
;     extern __shared__ __attribute__((aligned(16))) unsigned char lds_raw[];
;     LAS unsigned char* lds = (LAS unsigned char*)lds_raw;
;     cg::grid_group grid = cg::this_grid();
;     const int G = gridDim.x;
;     unsigned char* ws = a->ws;
;     bf16* XN = (bf16*)(ws + WS_XN); bf16* H = (bf16*)(ws + WS_H);
;     bf16* P = (bf16*)(ws + WS_P); const size_t BS = ROWBUF / 2;
;     bf16* MG = P + 5 * BS  ; bf16* ACT = P + BS;
;     ...
;     unsigned* ctl = (unsigned*)(ws + WS_CTL);
;     if (blockIdx.x == 0) for (int i = threadIdx.x; i < 4096; i += NTHREADS) __hip_atomic_store(ctl + i, 0u, __ATOMIC_RELAXED, __HIP_MEMORY_SCOPE_AGENT);
;     volatile LAS unsigned* xst = (volatile LAS unsigned*)(lds + LDS_BYTES - 64);
;     if (threadIdx.x < 2) xst[threadIdx.x] = 0u;
;     __syncthreads();
_Z14fwd_megakernel4Args:
	s_mov_b64 s[4:5], s[0:1]
	s_mov_b32 s98, 1
	s_nop 1
	v_writelane_b32 v255, s98, 54
	s_nop 1
	s_load_dwordx2 s[6:7], s[0:1], 0x90
	v_and_b32_e32 v193, 0x3ff, v0
	s_waitcnt lgkmcnt(0)
	v_writelane_b32 v254, s6, 0
	s_nop 1
	v_writelane_b32 v254, s7, 1
	s_load_dwordx2 s[6:7], s[4:5], 0x80
	s_add_u32 s4, s0, 0x90
	s_waitcnt lgkmcnt(0)
	v_writelane_b32 v254, s6, 2
	s_nop 1
	v_writelane_b32 v254, s7, 3
	v_writelane_b32 v254, s0, 4
	s_addc_u32 s5, s1, 0
	s_cmp_lg_u32 s2, 0
	v_writelane_b32 v254, s1, 5
	v_writelane_b32 v254, s4, 6
	s_nop 1
	v_writelane_b32 v254, s5, 7
	v_writelane_b32 v254, s2, 8
	s_cbranch_scc1 .LBB0_1
	s_getpc_b64 s[98:99]

;     __host__ __device__ void init(int M, int N, int K, long L_) { base.init(M, N, 1, 0, K); L = L_; }
;     __host__ __device__ void init(int M0, int Mtot, int N, int K, int G_, int c_) { base.init(M0, N, G_, c_, K); nrest = ((Mtot - M0) / BM) * NN * S; nkp = (K / BK) / S; G = G_; c = c_; }
; __device__ __forceinline__ int bxl() { int b = blockIdx.x; asm volatile("" : "+s"(b)); return b; }
; __device__ __forceinline__ ArgP argp() { ArgP p = (ArgP)__builtin_amdgcn_kernarg_segment_ptr(); asm volatile("" : "+s"(p)); return p; }
; template <class Epi, class Sched, bool ALIGN_EPI = false, bool SP2 = false>
; __device__ __forceinline__ void gemm_phase(PG8_LAS unsigned char* lds, const Gemm g, const Sched& S, const Epi& E) {
;     ...
;         if constexpr (!Epi::AFTER_DRAIN) { E(acc, cur, wr, wc, fr, fq); S.done(cur); }
; __global__ void __launch_bounds__(NTHREADS, 2) fwd_megakernel(Args a_) {
;     ...
;             pg8::Gemm g{MG, (const bf16*)(wl + W_O), MP, DM, DM}; pg8::SplitOrder<4, DM / 256> S; S.init(R_META, MP, DM, DM, G, bxl());
;             pg8::EpiResid E{l == 0 ? argp()->in[I_XP] : (const float*)nullptr, H, (bf16*)(ws + WS_P + 6 * ROWBUF), DM / 64, R_META, MP - R_META};
;             pg8::gemm_phase<pg8::EpiResid, pg8::SplitOrder<4, DM / 256>, true, true>(lds, g, S, E);
.Lp4_sig:
	v_readlane_b32 s8, v255, 54
	v_readlane_b32 s9, v254, 8
	v_readlane_b32 s26, v254, 10
	v_readlane_b32 s27, v254, 11
	v_readlane_b32 s28, v255, 6
	s_cmp_eq_u32 s8, 0
	s_cbranch_scc1 .Lp4_done
	s_cmp_ge_u32 s9, 0xc0
	s_cbranch_scc1 .Lp4_done
	s_and_b32 s8, s9, 7
	s_lshl_b32 s8, s8, 3
	s_bfe_u32 s9, s9, 0x30003
	s_add_i32 s8, s8, s9
	s_lshl_b32 s28, s28, 6
	s_add_i32 s8, s8, s28
	s_addk_i32 s8, 0xe80
	s_lshl_b32 s8, s8, 2
	v_mov_b32_e32 v150, s8
	v_mov_b32_e32 v151, 1
	s_waitcnt vmcnt(0)
	s_mov_b64 s[28:29], exec
	s_mov_b64 exec, 1
	global_atomic_add v150, v151, s[26:27]
	s_mov_b64 exec, s[28:29]
	s_branch .Lp4_done

; __device__ __forceinline__ void rms_row(const f32x4 (&v)[4], const float* g, int lane, float& rs, f32x4 (&y)[4]) {
;     float s = 0.f;
; #pragma unroll
;     for (int j = 0; j < 4; ++j) s += (v[j].x * v[j].x + v[j].y * v[j].y) + (v[j].z * v[j].z + v[j].w * v[j].w);
;     rs = __builtin_amdgcn_rsqf(wave_sum(s) * (1.f / DM) + EPS);
; #pragma unroll
;     for (int j = 0; j < 4; ++j) { const f32x4 gv = *((const f32x4*)g + lane + 64 * j); y[j] = v[j] * rs * gv; }
; }
; template <int NSLICE> __device__ __forceinline__ void rms_phase(ArgP a, const float* g, bool final_out, int G) {
;     ...
;     for (int m = gw; m < R_META; m += 2 * NGW) {
;         const int m2 = m + NGW; const bool has2 = m2 < R_META;
;         f32x4 v[4], u[4];
;         load_bf16_row(H + (size_t)m * DM, lane, v); load_bf16_row(H + (size_t)(has2 ? m2 : m) * DM, lane, u);
;         float rs; f32x4 y[4];
;         rms_row(v, g, lane, rs, y);
;         if (!final_out) store_bf16_row(XN + (size_t)m * DM, lane, y);
.LBB0_1009:
	v_readlane_b32 s60, v255, 54
	v_readlane_b32 s61, v254, 8
	s_nop 1
	s_cmp_eq_u32 s60, 0
	s_cbranch_scc1 .Lf4_skip
	s_cmp_lt_u32 s61, 0xc0
	s_cbranch_scc1 .Lf4_skip
	s_and_b32 s64, s61, 7
	s_lshl_b32 s64, s64, 3
	s_bfe_u32 s65, s61, 0x30003
	s_add_i32 s64, s64, s65
	v_readlane_b32 s65, v255, 6
	v_readlane_b32 s68, v254, 10
	v_readlane_b32 s69, v254, 11
	v_readlane_b32 s62, v254, 2
	v_readlane_b32 s63, v254, 3
	v_readlane_b32 s60, v254, 4
	v_readlane_b32 s61, v254, 5
	s_nop 1
	s_load_dwordx2 s[66:67], s[60:61], 0x58
	s_lshl_b32 s70, s65, 6
	s_add_i32 s70, s70, s64
	s_addk_i32 s70, 0xe80
	s_lshl_b32 s70, s70, 2
	s_add_u32 s68, s68, s70
	s_addc_u32 s69, s69, 0
	s_lshl_b32 s71, s65, 12
	v_and_b32_e32 v182, 63, v193
	v_lshlrev_b32_e32 v184, 4, v182
	v_lshlrev_b32_e32 v186, 5, v182
	v_xor_b32_e32 v176, 1, v182
	v_lshlrev_b32_e32 v176, 2, v176
	v_xor_b32_e32 v177, 2, v182
	v_lshlrev_b32_e32 v177, 2, v177
	v_xor_b32_e32 v178, 4, v182
	v_lshlrev_b32_e32 v178, 2, v178
	v_xor_b32_e32 v179, 8, v182
	v_lshlrev_b32_e32 v179, 2, v179
	v_xor_b32_e32 v180, 16, v182
	v_lshlrev_b32_e32 v180, 2, v180
	v_xor_b32_e32 v181, 32, v182
	v_lshlrev_b32_e32 v181, 2, v181
	v_readfirstlane_b32 s72, v193
	s_lshr_b32 s72, s72, 6
	s_waitcnt lgkmcnt(0)
	s_add_u32 s66, s66, s71
	s_addc_u32 s67, s67, 0
	global_load_dwordx4 v[0:3], v186, s[66:67]
	global_load_dwordx4 v[4:7], v186, s[66:67] offset:16
	global_load_dwordx4 v[8:11], v186, s[66:67] offset:2048
	global_load_dwordx4 v[12:15], v186, s[66:67] offset:2064
	s_cmp_lg_u32 s72, 0
	s_cbranch_scc1 .Lf4_polled
	v_mov_b32_e32 v187, 0
	s_mov_b32 s73, 0x60
	s_mov_b64 s[74:75], exec
	s_mov_b64 exec, 1
.Lf4_poll:
	global_atomic_add v188, v187, v189, s[68:69] sc0
	s_waitcnt vmcnt(0)
	v_readfirstlane_b32 s81, v188
	s_cmp_ge_u32 s81, 24
	s_cbranch_scc1 .Lf4_pollx
	s_sleep 2
	s_sub_u32 s73, s73, 1
	s_cmp_lg_u32 s73, 0
	s_cbranch_scc1 .Lf4_poll
.Lf4_pollx:
	s_mov_b64 exec, s[74:75]
.Lf4_polled:
	s_barrier
	buffer_inv sc1
	s_lshl_b32 s64, s64, 19
	s_lshl_b32 s72, s72, 16
	s_add_u32 s64, s64, s72
	s_add_u32 s76, s62, 0x7580000
	s_addc_u32 s77, s63, 0
	s_add_u32 s76, s76, s64
	s_addc_u32 s77, s77, 0
	s_add_u32 s78, s62, 0x5300000
	s_addc_u32 s79, s63, 0
	s_add_u32 s78, s78, s64
	s_addc_u32 s79, s79, 0
	s_mov_b32 s80, 4
.Lf4_batch:
	s_mov_b64 s[72:73], s[76:77]
	global_load_dwordx4 v[16:19], v184, s[72:73]
	global_load_dwordx4 v[20:23], v184, s[72:73] offset:1024
	s_add_u32 s72, s76, 0x800
	s_addc_u32 s73, s77, 0
	global_load_dwordx4 v[24:27], v184, s[72:73]
	global_load_dwordx4 v[28:31], v184, s[72:73] offset:1024
	s_add_u32 s72, s76, 0x1000
	s_addc_u32 s73, s77, 0
	global_load_dwordx4 v[32:35], v184, s[72:73]
	global_load_dwordx4 v[36:39], v184, s[72:73] offset:1024
	s_add_u32 s72, s76, 0x1800
	s_addc_u32 s73, s77, 0
	global_load_dwordx4 v[40:43], v184, s[72:73]
	global_load_dwordx4 v[44:47], v184, s[72:73] offset:1024
	s_add_u32 s72, s76, 0x2000
	s_addc_u32 s73, s77, 0
	global_load_dwordx4 v[48:51], v184, s[72:73]
	global_load_dwordx4 v[52:55], v184, s[72:73] offset:1024
	s_add_u32 s72, s76, 0x2800
	s_addc_u32 s73, s77, 0
	global_load_dwordx4 v[56:59], v184, s[72:73]
	global_load_dwordx4 v[60:63], v184, s[72:73] offset:1024
	s_add_u32 s72, s76, 0x3000
	s_addc_u32 s73, s77, 0
	global_load_dwordx4 v[64:67], v184, s[72:73]
	global_load_dwordx4 v[68:71], v184, s[72:73] offset:1024
	s_add_u32 s72, s76, 0x3800
	s_addc_u32 s73, s77, 0
	global_load_dwordx4 v[72:75], v184, s[72:73]
	global_load_dwordx4 v[76:79], v184, s[72:73] offset:1024
	s_waitcnt vmcnt(8)
	v_lshlrev_b32_e32 v210, 16, v16
	v_and_b32_e32 v211, 0xffff0000, v16
	v_mul_f32_e32 v212, v210, v210
	v_mul_f32_e32 v213, v211, v211
	v_lshlrev_b32_e32 v214, 16, v24
	v_and_b32_e32 v215, 0xffff0000, v24
	v_mul_f32_e32 v216, v214, v214
	v_mul_f32_e32 v217, v215, v215
	v_lshlrev_b32_e32 v218, 16, v32
	v_and_b32_e32 v219, 0xffff0000, v32
	v_mul_f32_e32 v220, v218, v218
	v_mul_f32_e32 v221, v219, v219
	v_lshlrev_b32_e32 v222, 16, v40
	v_and_b32_e32 v223, 0xffff0000, v40
	v_mul_f32_e32 v224, v222, v222
	v_mul_f32_e32 v225, v223, v223
	v_lshlrev_b32_e32 v210, 16, v17
	v_and_b32_e32 v211, 0xffff0000, v17
	v_fmac_f32_e32 v212, v210, v210
	v_fmac_f32_e32 v213, v211, v211
	v_lshlrev_b32_e32 v214, 16, v25
	v_and_b32_e32 v215, 0xffff0000, v25
	v_fmac_f32_e32 v216, v214, v214
	v_fmac_f32_e32 v217, v215, v215
	v_lshlrev_b32_e32 v218, 16, v33
	v_and_b32_e32 v219, 0xffff0000, v33
	v_fmac_f32_e32 v220, v218, v218
	v_fmac_f32_e32 v221, v219, v219
	v_lshlrev_b32_e32 v222, 16, v41
	v_and_b32_e32 v223, 0xffff0000, v41
	v_fmac_f32_e32 v224, v222, v222
	v_fmac_f32_e32 v225, v223, v223
	v_lshlrev_b32_e32 v210, 16, v18
	v_and_b32_e32 v211, 0xffff0000, v18
	v_fmac_f32_e32 v212, v210, v210
	v_fmac_f32_e32 v213, v211, v211
	v_lshlrev_b32_e32 v214, 16, v26
	v_and_b32_e32 v215, 0xffff0000, v26
	v_fmac_f32_e32 v216, v214, v214
	v_fmac_f32_e32 v217, v215, v215
	v_lshlrev_b32_e32 v218, 16, v34
	v_and_b32_e32 v219, 0xffff0000, v34
	v_fmac_f32_e32 v220, v218, v218
	v_fmac_f32_e32 v221, v219, v219
	v_lshlrev_b32_e32 v222, 16, v42
	v_and_b32_e32 v223, 0xffff0000, v42
	v_fmac_f32_e32 v224, v222, v222
	v_fmac_f32_e32 v225, v223, v223
	v_lshlrev_b32_e32 v210, 16, v19
	v_and_b32_e32 v211, 0xffff0000, v19
	v_fmac_f32_e32 v212, v210, v210
	v_fmac_f32_e32 v213, v211, v211
	v_lshlrev_b32_e32 v214, 16, v27
	v_and_b32_e32 v215, 0xffff0000, v27
	v_fmac_f32_e32 v216, v214, v214
	v_fmac_f32_e32 v217, v215, v215
	v_lshlrev_b32_e32 v218, 16, v35
	v_and_b32_e32 v219, 0xffff0000, v35
	v_fmac_f32_e32 v220, v218, v218
	v_fmac_f32_e32 v221, v219, v219
	v_lshlrev_b32_e32 v222, 16, v43
	v_and_b32_e32 v223, 0xffff0000, v43
; __device__ __forceinline__ float wave_sum(float v) {
; #pragma unroll
;     for (int o = 1; o < 64; o <<= 1) v += __shfl_xor(v, o);
;     return v;
; }
; __device__ __forceinline__ void rms_row(const f32x4 (&v)[4], const float* g, int lane, float& rs, f32x4 (&y)[4]) {
;     float s = 0.f;
; #pragma unroll
;     for (int j = 0; j < 4; ++j) s += (v[j].x * v[j].x + v[j].y * v[j].y) + (v[j].z * v[j].z + v[j].w * v[j].w);
;     rs = __builtin_amdgcn_rsqf(wave_sum(s) * (1.f / DM) + EPS);
; #pragma unroll
;     for (int j = 0; j < 4; ++j) { const f32x4 gv = *((const f32x4*)g + lane + 64 * j); y[j] = v[j] * rs * gv; }
; }
	v_fmac_f32_e32 v224, v222, v222
	v_fmac_f32_e32 v225, v223, v223
	v_lshlrev_b32_e32 v210, 16, v20
	v_and_b32_e32 v211, 0xffff0000, v20
	v_fmac_f32_e32 v212, v210, v210
	v_fmac_f32_e32 v213, v211, v211
	v_lshlrev_b32_e32 v214, 16, v28
	v_and_b32_e32 v215, 0xffff0000, v28
	v_fmac_f32_e32 v216, v214, v214
	v_fmac_f32_e32 v217, v215, v215
	v_lshlrev_b32_e32 v218, 16, v36
	v_and_b32_e32 v219, 0xffff0000, v36
	v_fmac_f32_e32 v220, v218, v218
	v_fmac_f32_e32 v221, v219, v219
	v_lshlrev_b32_e32 v222, 16, v44
	v_and_b32_e32 v223, 0xffff0000, v44
	v_fmac_f32_e32 v224, v222, v222
	v_fmac_f32_e32 v225, v223, v223
	v_lshlrev_b32_e32 v210, 16, v21
	v_and_b32_e32 v211, 0xffff0000, v21
	v_fmac_f32_e32 v212, v210, v210
	v_fmac_f32_e32 v213, v211, v211
	v_lshlrev_b32_e32 v214, 16, v29
	v_and_b32_e32 v215, 0xffff0000, v29
	v_fmac_f32_e32 v216, v214, v214
	v_fmac_f32_e32 v217, v215, v215
	v_lshlrev_b32_e32 v218, 16, v37
	v_and_b32_e32 v219, 0xffff0000, v37
	v_fmac_f32_e32 v220, v218, v218
	v_fmac_f32_e32 v221, v219, v219
	v_lshlrev_b32_e32 v222, 16, v45
	v_and_b32_e32 v223, 0xffff0000, v45
	v_fmac_f32_e32 v224, v222, v222
	v_fmac_f32_e32 v225, v223, v223
	v_lshlrev_b32_e32 v210, 16, v22
	v_and_b32_e32 v211, 0xffff0000, v22
	v_fmac_f32_e32 v212, v210, v210
	v_fmac_f32_e32 v213, v211, v211
	v_lshlrev_b32_e32 v214, 16, v30
	v_and_b32_e32 v215, 0xffff0000, v30
	v_fmac_f32_e32 v216, v214, v214
	v_fmac_f32_e32 v217, v215, v215
	v_lshlrev_b32_e32 v218, 16, v38
	v_and_b32_e32 v219, 0xffff0000, v38
	v_fmac_f32_e32 v220, v218, v218
	v_fmac_f32_e32 v221, v219, v219
	v_lshlrev_b32_e32 v222, 16, v46
	v_and_b32_e32 v223, 0xffff0000, v46
	v_fmac_f32_e32 v224, v222, v222
	v_fmac_f32_e32 v225, v223, v223
	v_lshlrev_b32_e32 v210, 16, v23
	v_and_b32_e32 v211, 0xffff0000, v23
	v_fmac_f32_e32 v212, v210, v210
	v_fmac_f32_e32 v213, v211, v211
	v_lshlrev_b32_e32 v214, 16, v31
	v_and_b32_e32 v215, 0xffff0000, v31
	v_fmac_f32_e32 v216, v214, v214
	v_fmac_f32_e32 v217, v215, v215
	v_lshlrev_b32_e32 v218, 16, v39
	v_and_b32_e32 v219, 0xffff0000, v39
	v_fmac_f32_e32 v220, v218, v218
	v_fmac_f32_e32 v221, v219, v219
	v_lshlrev_b32_e32 v222, 16, v47
	v_and_b32_e32 v223, 0xffff0000, v47
	v_fmac_f32_e32 v224, v222, v222
	v_fmac_f32_e32 v225, v223, v223
	v_add_f32_e32 v212, v212, v213
	v_add_f32_e32 v216, v216, v217
	v_add_f32_e32 v220, v220, v221
	v_add_f32_e32 v224, v224, v225
	ds_bpermute_b32 v210, v176, v212
	ds_bpermute_b32 v214, v176, v216
	ds_bpermute_b32 v218, v176, v220
	ds_bpermute_b32 v222, v176, v224
	s_waitcnt lgkmcnt(0)
	v_add_f32_e32 v212, v212, v210
	v_add_f32_e32 v216, v216, v214
	v_add_f32_e32 v220, v220, v218
	v_add_f32_e32 v224, v224, v222
	ds_bpermute_b32 v210, v177, v212
	ds_bpermute_b32 v214, v177, v216
	ds_bpermute_b32 v218, v177, v220
	ds_bpermute_b32 v222, v177, v224
	s_waitcnt lgkmcnt(0)
	v_add_f32_e32 v212, v212, v210
	v_add_f32_e32 v216, v216, v214
	v_add_f32_e32 v220, v220, v218
	v_add_f32_e32 v224, v224, v222
	ds_bpermute_b32 v210, v178, v212
	ds_bpermute_b32 v214, v178, v216
	ds_bpermute_b32 v218, v178, v220
	ds_bpermute_b32 v222, v178, v224
	s_waitcnt lgkmcnt(0)
	v_add_f32_e32 v212, v212, v210
	v_add_f32_e32 v216, v216, v214
	v_add_f32_e32 v220, v220, v218
	v_add_f32_e32 v224, v224, v222
	ds_bpermute_b32 v210, v179, v212
	ds_bpermute_b32 v214, v179, v216
	ds_bpermute_b32 v218, v179, v220
	ds_bpermute_b32 v222, v179, v224
	s_waitcnt lgkmcnt(0)
	v_add_f32_e32 v212, v212, v210
	v_add_f32_e32 v216, v216, v214
	v_add_f32_e32 v220, v220, v218
	v_add_f32_e32 v224, v224, v222
	ds_bpermute_b32 v210, v180, v212
	ds_bpermute_b32 v214, v180, v216
	ds_bpermute_b32 v218, v180, v220
	ds_bpermute_b32 v222, v180, v224
	s_waitcnt lgkmcnt(0)
	v_add_f32_e32 v212, v212, v210
	v_add_f32_e32 v216, v216, v214
	v_add_f32_e32 v220, v220, v218
	v_add_f32_e32 v224, v224, v222
	ds_bpermute_b32 v210, v181, v212
	ds_bpermute_b32 v214, v181, v216
	ds_bpermute_b32 v218, v181, v220
	ds_bpermute_b32 v222, v181, v224
	s_waitcnt lgkmcnt(0)
	v_add_f32_e32 v212, v212, v210
	v_add_f32_e32 v216, v216, v214
	v_add_f32_e32 v220, v220, v218
	v_add_f32_e32 v224, v224, v222
	v_fmamk_f32 v212, v212, 0x3a800000, v207
	v_fmamk_f32 v216, v216, 0x3a800000, v207
	v_fmamk_f32 v220, v220, 0x3a800000, v207
	v_fmamk_f32 v224, v224, 0x3a800000, v207
	v_rsq_f32_e32 v212, v212
	v_rsq_f32_e32 v216, v216
	v_rsq_f32_e32 v220, v220
	v_rsq_f32_e32 v224, v224
	s_nop 1
	v_lshlrev_b32_e32 v210, 16, v16
	v_and_b32_e32 v211, 0xffff0000, v16
	v_mul_f32_e32 v210, v210, v212
	v_mul_f32_e32 v211, v211, v212
	v_mul_f32_e32 v210, v210, v0
	v_mul_f32_e32 v211, v211, v1
	v_cvt_pk_bf16_f32 v16, v210, v211
	v_lshlrev_b32_e32 v210, 16, v17
	v_and_b32_e32 v211, 0xffff0000, v17
	v_mul_f32_e32 v210, v210, v212
	v_mul_f32_e32 v211, v211, v212
	v_mul_f32_e32 v210, v210, v2
	v_mul_f32_e32 v211, v211, v3
	v_cvt_pk_bf16_f32 v17, v210, v211
	v_lshlrev_b32_e32 v210, 16, v18
	v_and_b32_e32 v211, 0xffff0000, v18
	v_mul_f32_e32 v210, v210, v212
	v_mul_f32_e32 v211, v211, v212
	v_mul_f32_e32 v210, v210, v4
	v_mul_f32_e32 v211, v211, v5
	v_cvt_pk_bf16_f32 v18, v210, v211
	v_lshlrev_b32_e32 v210, 16, v19
	v_and_b32_e32 v211, 0xffff0000, v19
	v_mul_f32_e32 v210, v210, v212
	v_mul_f32_e32 v211, v211, v212
	v_mul_f32_e32 v210, v210, v6
	v_mul_f32_e32 v211, v211, v7
	v_cvt_pk_bf16_f32 v19, v210, v211
	v_lshlrev_b32_e32 v210, 16, v20
	v_and_b32_e32 v211, 0xffff0000, v20
	v_mul_f32_e32 v210, v210, v212
	v_mul_f32_e32 v211, v211, v212
	v_mul_f32_e32 v210, v210, v8
	v_mul_f32_e32 v211, v211, v9
	v_cvt_pk_bf16_f32 v20, v210, v211
	v_lshlrev_b32_e32 v210, 16, v21
	v_and_b32_e32 v211, 0xffff0000, v21
	v_mul_f32_e32 v210, v210, v212
	v_mul_f32_e32 v211, v211, v212
; __device__ __forceinline__ unsigned cvt_pk_bf16(float lo, float hi) { unsigned r; asm volatile("v_cvt_pk_bf16_f32 %0, %1, %2" : "=v"(r) : "v"(lo), "v"(hi)); return r; }
; __device__ __forceinline__ void rms_row(const f32x4 (&v)[4], const float* g, int lane, float& rs, f32x4 (&y)[4]) {
;     ...
;     for (int j = 0; j < 4; ++j) { const f32x4 gv = *((const f32x4*)g + lane + 64 * j); y[j] = v[j] * rs * gv; }
; }
; __device__ __forceinline__ void load_bf16_row(const bf16* row, int lane, f32x4 (&v)[4]) {
;     const u32x2* p = (const u32x2*)row + lane;
; #pragma unroll
;     for (int j = 0; j < 4; ++j) { const u32x2 w = p[64 * j]; v[j] = (f32x4){bflo(w.x), bfhi(w.x), bflo(w.y), bfhi(w.y)}; }
; }
; __device__ __forceinline__ void store_bf16_row(bf16* orow, int lane, const f32x4 (&y)[4]) {
;     u32x2* o8 = (u32x2*)orow + lane;
; #pragma unroll
;     for (int j = 0; j < 4; ++j) { u32x2 w; w.x = cvt_pk_bf16(y[j].x, y[j].y); w.y = cvt_pk_bf16(y[j].z, y[j].w); o8[64 * j] = w; }
; }
	v_mul_f32_e32 v210, v210, v10
	v_mul_f32_e32 v211, v211, v11
	v_cvt_pk_bf16_f32 v21, v210, v211
	v_lshlrev_b32_e32 v210, 16, v22
	v_and_b32_e32 v211, 0xffff0000, v22
	v_mul_f32_e32 v210, v210, v212
	v_mul_f32_e32 v211, v211, v212
	v_mul_f32_e32 v210, v210, v12
	v_mul_f32_e32 v211, v211, v13
	v_cvt_pk_bf16_f32 v22, v210, v211
	v_lshlrev_b32_e32 v210, 16, v23
	v_and_b32_e32 v211, 0xffff0000, v23
	v_mul_f32_e32 v210, v210, v212
	v_mul_f32_e32 v211, v211, v212
	v_mul_f32_e32 v210, v210, v14
	v_mul_f32_e32 v211, v211, v15
	v_cvt_pk_bf16_f32 v23, v210, v211
	s_mov_b64 s[72:73], s[78:79]
	global_store_dwordx4 v184, v[16:19], s[72:73]
	global_store_dwordx4 v184, v[20:23], s[72:73] offset:1024
	v_lshlrev_b32_e32 v214, 16, v24
	v_and_b32_e32 v215, 0xffff0000, v24
	v_mul_f32_e32 v214, v214, v216
	v_mul_f32_e32 v215, v215, v216
	v_mul_f32_e32 v214, v214, v0
	v_mul_f32_e32 v215, v215, v1
	v_cvt_pk_bf16_f32 v24, v214, v215
	v_lshlrev_b32_e32 v214, 16, v25
	v_and_b32_e32 v215, 0xffff0000, v25
	v_mul_f32_e32 v214, v214, v216
	v_mul_f32_e32 v215, v215, v216
	v_mul_f32_e32 v214, v214, v2
	v_mul_f32_e32 v215, v215, v3
	v_cvt_pk_bf16_f32 v25, v214, v215
	v_lshlrev_b32_e32 v214, 16, v26
	v_and_b32_e32 v215, 0xffff0000, v26
	v_mul_f32_e32 v214, v214, v216
	v_mul_f32_e32 v215, v215, v216
	v_mul_f32_e32 v214, v214, v4
	v_mul_f32_e32 v215, v215, v5
	v_cvt_pk_bf16_f32 v26, v214, v215
	v_lshlrev_b32_e32 v214, 16, v27
	v_and_b32_e32 v215, 0xffff0000, v27
	v_mul_f32_e32 v214, v214, v216
	v_mul_f32_e32 v215, v215, v216
	v_mul_f32_e32 v214, v214, v6
	v_mul_f32_e32 v215, v215, v7
	v_cvt_pk_bf16_f32 v27, v214, v215
	v_lshlrev_b32_e32 v214, 16, v28
	v_and_b32_e32 v215, 0xffff0000, v28
	v_mul_f32_e32 v214, v214, v216
	v_mul_f32_e32 v215, v215, v216
	v_mul_f32_e32 v214, v214, v8
	v_mul_f32_e32 v215, v215, v9
	v_cvt_pk_bf16_f32 v28, v214, v215
	v_lshlrev_b32_e32 v214, 16, v29
	v_and_b32_e32 v215, 0xffff0000, v29
	v_mul_f32_e32 v214, v214, v216
	v_mul_f32_e32 v215, v215, v216
	v_mul_f32_e32 v214, v214, v10
	v_mul_f32_e32 v215, v215, v11
	v_cvt_pk_bf16_f32 v29, v214, v215
	v_lshlrev_b32_e32 v214, 16, v30
	v_and_b32_e32 v215, 0xffff0000, v30
	v_mul_f32_e32 v214, v214, v216
	v_mul_f32_e32 v215, v215, v216
	v_mul_f32_e32 v214, v214, v12
	v_mul_f32_e32 v215, v215, v13
	v_cvt_pk_bf16_f32 v30, v214, v215
	v_lshlrev_b32_e32 v214, 16, v31
	v_and_b32_e32 v215, 0xffff0000, v31
	v_mul_f32_e32 v214, v214, v216
	v_mul_f32_e32 v215, v215, v216
	v_mul_f32_e32 v214, v214, v14
	v_mul_f32_e32 v215, v215, v15
	v_cvt_pk_bf16_f32 v31, v214, v215
	s_add_u32 s72, s78, 0x800
	s_addc_u32 s73, s79, 0
	global_store_dwordx4 v184, v[24:27], s[72:73]
	global_store_dwordx4 v184, v[28:31], s[72:73] offset:1024
	v_lshlrev_b32_e32 v218, 16, v32
	v_and_b32_e32 v219, 0xffff0000, v32
	v_mul_f32_e32 v218, v218, v220
	v_mul_f32_e32 v219, v219, v220
	v_mul_f32_e32 v218, v218, v0
	v_mul_f32_e32 v219, v219, v1
	v_cvt_pk_bf16_f32 v32, v218, v219
	v_lshlrev_b32_e32 v218, 16, v33
	v_and_b32_e32 v219, 0xffff0000, v33
	v_mul_f32_e32 v218, v218, v220
	v_mul_f32_e32 v219, v219, v220
	v_mul_f32_e32 v218, v218, v2
	v_mul_f32_e32 v219, v219, v3
	v_cvt_pk_bf16_f32 v33, v218, v219
	v_lshlrev_b32_e32 v218, 16, v34
	v_and_b32_e32 v219, 0xffff0000, v34
	v_mul_f32_e32 v218, v218, v220
	v_mul_f32_e32 v219, v219, v220
	v_mul_f32_e32 v218, v218, v4
	v_mul_f32_e32 v219, v219, v5
	v_cvt_pk_bf16_f32 v34, v218, v219
	v_lshlrev_b32_e32 v218, 16, v35
	v_and_b32_e32 v219, 0xffff0000, v35
	v_mul_f32_e32 v218, v218, v220
	v_mul_f32_e32 v219, v219, v220
	v_mul_f32_e32 v218, v218, v6
	v_mul_f32_e32 v219, v219, v7
	v_cvt_pk_bf16_f32 v35, v218, v219
	v_lshlrev_b32_e32 v218, 16, v36
	v_and_b32_e32 v219, 0xffff0000, v36
	v_mul_f32_e32 v218, v218, v220
	v_mul_f32_e32 v219, v219, v220
	v_mul_f32_e32 v218, v218, v8
	v_mul_f32_e32 v219, v219, v9
	v_cvt_pk_bf16_f32 v36, v218, v219
	v_lshlrev_b32_e32 v218, 16, v37
	v_and_b32_e32 v219, 0xffff0000, v37
	v_mul_f32_e32 v218, v218, v220
	v_mul_f32_e32 v219, v219, v220
	v_mul_f32_e32 v218, v218, v10
	v_mul_f32_e32 v219, v219, v11
	v_cvt_pk_bf16_f32 v37, v218, v219
	v_lshlrev_b32_e32 v218, 16, v38
	v_and_b32_e32 v219, 0xffff0000, v38
	v_mul_f32_e32 v218, v218, v220
	v_mul_f32_e32 v219, v219, v220
	v_mul_f32_e32 v218, v218, v12
	v_mul_f32_e32 v219, v219, v13
	v_cvt_pk_bf16_f32 v38, v218, v219
	v_lshlrev_b32_e32 v218, 16, v39
	v_and_b32_e32 v219, 0xffff0000, v39
	v_mul_f32_e32 v218, v218, v220
	v_mul_f32_e32 v219, v219, v220
	v_mul_f32_e32 v218, v218, v14
	v_mul_f32_e32 v219, v219, v15
	v_cvt_pk_bf16_f32 v39, v218, v219
	s_add_u32 s72, s78, 0x1000
	s_addc_u32 s73, s79, 0
	global_store_dwordx4 v184, v[32:35], s[72:73]
	global_store_dwordx4 v184, v[36:39], s[72:73] offset:1024
	v_lshlrev_b32_e32 v222, 16, v40
	v_and_b32_e32 v223, 0xffff0000, v40
	v_mul_f32_e32 v222, v222, v224
	v_mul_f32_e32 v223, v223, v224
	v_mul_f32_e32 v222, v222, v0
	v_mul_f32_e32 v223, v223, v1
	v_cvt_pk_bf16_f32 v40, v222, v223
	v_lshlrev_b32_e32 v222, 16, v41
	v_and_b32_e32 v223, 0xffff0000, v41
	v_mul_f32_e32 v222, v222, v224
	v_mul_f32_e32 v223, v223, v224
	v_mul_f32_e32 v222, v222, v2
	v_mul_f32_e32 v223, v223, v3
	v_cvt_pk_bf16_f32 v41, v222, v223
	v_lshlrev_b32_e32 v222, 16, v42
	v_and_b32_e32 v223, 0xffff0000, v42
	v_mul_f32_e32 v222, v222, v224
	v_mul_f32_e32 v223, v223, v224
	v_mul_f32_e32 v222, v222, v4
	v_mul_f32_e32 v223, v223, v5
	v_cvt_pk_bf16_f32 v42, v222, v223
	v_lshlrev_b32_e32 v222, 16, v43
	v_and_b32_e32 v223, 0xffff0000, v43
	v_mul_f32_e32 v222, v222, v224
	v_mul_f32_e32 v223, v223, v224
	v_mul_f32_e32 v222, v222, v6
	v_mul_f32_e32 v223, v223, v7
	v_cvt_pk_bf16_f32 v43, v222, v223
	v_lshlrev_b32_e32 v222, 16, v44
	v_and_b32_e32 v223, 0xffff0000, v44
	v_mul_f32_e32 v222, v222, v224
	v_mul_f32_e32 v223, v223, v224
	v_mul_f32_e32 v222, v222, v8
	v_mul_f32_e32 v223, v223, v9
	v_cvt_pk_bf16_f32 v44, v222, v223
	v_lshlrev_b32_e32 v222, 16, v45
	v_and_b32_e32 v223, 0xffff0000, v45
	v_mul_f32_e32 v222, v222, v224
	v_mul_f32_e32 v223, v223, v224
	v_mul_f32_e32 v222, v222, v10
	v_mul_f32_e32 v223, v223, v11
	v_cvt_pk_bf16_f32 v45, v222, v223
	v_lshlrev_b32_e32 v222, 16, v46
	v_and_b32_e32 v223, 0xffff0000, v46
	v_mul_f32_e32 v222, v222, v224
	v_mul_f32_e32 v223, v223, v224
	v_mul_f32_e32 v222, v222, v12
	v_mul_f32_e32 v223, v223, v13
	v_cvt_pk_bf16_f32 v46, v222, v223
	v_lshlrev_b32_e32 v222, 16, v47
	v_and_b32_e32 v223, 0xffff0000, v47
	v_mul_f32_e32 v222, v222, v224
	v_mul_f32_e32 v223, v223, v224
	v_mul_f32_e32 v222, v222, v14
	v_mul_f32_e32 v223, v223, v15
	v_cvt_pk_bf16_f32 v47, v222, v223
	s_add_u32 s72, s78, 0x1800
	s_addc_u32 s73, s79, 0
	global_store_dwordx4 v184, v[40:43], s[72:73]
	global_store_dwordx4 v184, v[44:47], s[72:73] offset:1024
	s_waitcnt vmcnt(8)
; __device__ __forceinline__ float wave_sum(float v) {
; #pragma unroll
;     for (int o = 1; o < 64; o <<= 1) v += __shfl_xor(v, o);
;     return v;
; }
; __device__ __forceinline__ void rms_row(const f32x4 (&v)[4], const float* g, int lane, float& rs, f32x4 (&y)[4]) {
;     float s = 0.f;
; #pragma unroll
;     for (int j = 0; j < 4; ++j) s += (v[j].x * v[j].x + v[j].y * v[j].y) + (v[j].z * v[j].z + v[j].w * v[j].w);
;     rs = __builtin_amdgcn_rsqf(wave_sum(s) * (1.f / DM) + EPS);
	v_lshlrev_b32_e32 v210, 16, v48
	v_and_b32_e32 v211, 0xffff0000, v48
	v_mul_f32_e32 v212, v210, v210
	v_mul_f32_e32 v213, v211, v211
	v_lshlrev_b32_e32 v214, 16, v56
	v_and_b32_e32 v215, 0xffff0000, v56
	v_mul_f32_e32 v216, v214, v214
	v_mul_f32_e32 v217, v215, v215
	v_lshlrev_b32_e32 v218, 16, v64
	v_and_b32_e32 v219, 0xffff0000, v64
	v_mul_f32_e32 v220, v218, v218
	v_mul_f32_e32 v221, v219, v219
	v_lshlrev_b32_e32 v222, 16, v72
	v_and_b32_e32 v223, 0xffff0000, v72
	v_mul_f32_e32 v224, v222, v222
	v_mul_f32_e32 v225, v223, v223
	v_lshlrev_b32_e32 v210, 16, v49
	v_and_b32_e32 v211, 0xffff0000, v49
	v_fmac_f32_e32 v212, v210, v210
	v_fmac_f32_e32 v213, v211, v211
	v_lshlrev_b32_e32 v214, 16, v57
	v_and_b32_e32 v215, 0xffff0000, v57
	v_fmac_f32_e32 v216, v214, v214
	v_fmac_f32_e32 v217, v215, v215
	v_lshlrev_b32_e32 v218, 16, v65
	v_and_b32_e32 v219, 0xffff0000, v65
	v_fmac_f32_e32 v220, v218, v218
	v_fmac_f32_e32 v221, v219, v219
	v_lshlrev_b32_e32 v222, 16, v73
	v_and_b32_e32 v223, 0xffff0000, v73
	v_fmac_f32_e32 v224, v222, v222
	v_fmac_f32_e32 v225, v223, v223
	v_lshlrev_b32_e32 v210, 16, v50
	v_and_b32_e32 v211, 0xffff0000, v50
	v_fmac_f32_e32 v212, v210, v210
	v_fmac_f32_e32 v213, v211, v211
	v_lshlrev_b32_e32 v214, 16, v58
	v_and_b32_e32 v215, 0xffff0000, v58
	v_fmac_f32_e32 v216, v214, v214
	v_fmac_f32_e32 v217, v215, v215
	v_lshlrev_b32_e32 v218, 16, v66
	v_and_b32_e32 v219, 0xffff0000, v66
	v_fmac_f32_e32 v220, v218, v218
	v_fmac_f32_e32 v221, v219, v219
	v_lshlrev_b32_e32 v222, 16, v74
	v_and_b32_e32 v223, 0xffff0000, v74
	v_fmac_f32_e32 v224, v222, v222
	v_fmac_f32_e32 v225, v223, v223
	v_lshlrev_b32_e32 v210, 16, v51
	v_and_b32_e32 v211, 0xffff0000, v51
	v_fmac_f32_e32 v212, v210, v210
	v_fmac_f32_e32 v213, v211, v211
	v_lshlrev_b32_e32 v214, 16, v59
	v_and_b32_e32 v215, 0xffff0000, v59
	v_fmac_f32_e32 v216, v214, v214
	v_fmac_f32_e32 v217, v215, v215
	v_lshlrev_b32_e32 v218, 16, v67
	v_and_b32_e32 v219, 0xffff0000, v67
	v_fmac_f32_e32 v220, v218, v218
	v_fmac_f32_e32 v221, v219, v219
	v_lshlrev_b32_e32 v222, 16, v75
	v_and_b32_e32 v223, 0xffff0000, v75
	v_fmac_f32_e32 v224, v222, v222
	v_fmac_f32_e32 v225, v223, v223
	v_lshlrev_b32_e32 v210, 16, v52
	v_and_b32_e32 v211, 0xffff0000, v52
	v_fmac_f32_e32 v212, v210, v210
	v_fmac_f32_e32 v213, v211, v211
	v_lshlrev_b32_e32 v214, 16, v60
	v_and_b32_e32 v215, 0xffff0000, v60
	v_fmac_f32_e32 v216, v214, v214
	v_fmac_f32_e32 v217, v215, v215
	v_lshlrev_b32_e32 v218, 16, v68
	v_and_b32_e32 v219, 0xffff0000, v68
	v_fmac_f32_e32 v220, v218, v218
	v_fmac_f32_e32 v221, v219, v219
	v_lshlrev_b32_e32 v222, 16, v76
	v_and_b32_e32 v223, 0xffff0000, v76
	v_fmac_f32_e32 v224, v222, v222
	v_fmac_f32_e32 v225, v223, v223
	v_lshlrev_b32_e32 v210, 16, v53
	v_and_b32_e32 v211, 0xffff0000, v53
	v_fmac_f32_e32 v212, v210, v210
	v_fmac_f32_e32 v213, v211, v211
	v_lshlrev_b32_e32 v214, 16, v61
	v_and_b32_e32 v215, 0xffff0000, v61
	v_fmac_f32_e32 v216, v214, v214
	v_fmac_f32_e32 v217, v215, v215
	v_lshlrev_b32_e32 v218, 16, v69
	v_and_b32_e32 v219, 0xffff0000, v69
	v_fmac_f32_e32 v220, v218, v218
	v_fmac_f32_e32 v221, v219, v219
	v_lshlrev_b32_e32 v222, 16, v77
	v_and_b32_e32 v223, 0xffff0000, v77
	v_fmac_f32_e32 v224, v222, v222
	v_fmac_f32_e32 v225, v223, v223
	v_lshlrev_b32_e32 v210, 16, v54
	v_and_b32_e32 v211, 0xffff0000, v54
	v_fmac_f32_e32 v212, v210, v210
	v_fmac_f32_e32 v213, v211, v211
	v_lshlrev_b32_e32 v214, 16, v62
	v_and_b32_e32 v215, 0xffff0000, v62
	v_fmac_f32_e32 v216, v214, v214
	v_fmac_f32_e32 v217, v215, v215
	v_lshlrev_b32_e32 v218, 16, v70
	v_and_b32_e32 v219, 0xffff0000, v70
	v_fmac_f32_e32 v220, v218, v218
	v_fmac_f32_e32 v221, v219, v219
	v_lshlrev_b32_e32 v222, 16, v78
	v_and_b32_e32 v223, 0xffff0000, v78
	v_fmac_f32_e32 v224, v222, v222
	v_fmac_f32_e32 v225, v223, v223
	v_lshlrev_b32_e32 v210, 16, v55
	v_and_b32_e32 v211, 0xffff0000, v55
	v_fmac_f32_e32 v212, v210, v210
	v_fmac_f32_e32 v213, v211, v211
	v_lshlrev_b32_e32 v214, 16, v63
	v_and_b32_e32 v215, 0xffff0000, v63
	v_fmac_f32_e32 v216, v214, v214
	v_fmac_f32_e32 v217, v215, v215
	v_lshlrev_b32_e32 v218, 16, v71
	v_and_b32_e32 v219, 0xffff0000, v71
	v_fmac_f32_e32 v220, v218, v218
	v_fmac_f32_e32 v221, v219, v219
	v_lshlrev_b32_e32 v222, 16, v79
	v_and_b32_e32 v223, 0xffff0000, v79
	v_fmac_f32_e32 v224, v222, v222
	v_fmac_f32_e32 v225, v223, v223
	v_add_f32_e32 v212, v212, v213
	v_add_f32_e32 v216, v216, v217
	v_add_f32_e32 v220, v220, v221
	v_add_f32_e32 v224, v224, v225
	ds_bpermute_b32 v210, v176, v212
	ds_bpermute_b32 v214, v176, v216
	ds_bpermute_b32 v218, v176, v220
	ds_bpermute_b32 v222, v176, v224
	s_waitcnt lgkmcnt(0)
	v_add_f32_e32 v212, v212, v210
	v_add_f32_e32 v216, v216, v214
	v_add_f32_e32 v220, v220, v218
	v_add_f32_e32 v224, v224, v222
	ds_bpermute_b32 v210, v177, v212
	ds_bpermute_b32 v214, v177, v216
	ds_bpermute_b32 v218, v177, v220
	ds_bpermute_b32 v222, v177, v224
	s_waitcnt lgkmcnt(0)
	v_add_f32_e32 v212, v212, v210
	v_add_f32_e32 v216, v216, v214
	v_add_f32_e32 v220, v220, v218
	v_add_f32_e32 v224, v224, v222
	ds_bpermute_b32 v210, v178, v212
	ds_bpermute_b32 v214, v178, v216
	ds_bpermute_b32 v218, v178, v220
	ds_bpermute_b32 v222, v178, v224
	s_waitcnt lgkmcnt(0)
	v_add_f32_e32 v212, v212, v210
	v_add_f32_e32 v216, v216, v214
	v_add_f32_e32 v220, v220, v218
	v_add_f32_e32 v224, v224, v222
	ds_bpermute_b32 v210, v179, v212
	ds_bpermute_b32 v214, v179, v216
	ds_bpermute_b32 v218, v179, v220
	ds_bpermute_b32 v222, v179, v224
	s_waitcnt lgkmcnt(0)
	v_add_f32_e32 v212, v212, v210
	v_add_f32_e32 v216, v216, v214
	v_add_f32_e32 v220, v220, v218
	v_add_f32_e32 v224, v224, v222
	ds_bpermute_b32 v210, v180, v212
	ds_bpermute_b32 v214, v180, v216
	ds_bpermute_b32 v218, v180, v220
	ds_bpermute_b32 v222, v180, v224
	s_waitcnt lgkmcnt(0)
; __device__ __forceinline__ unsigned cvt_pk_bf16(float lo, float hi) { unsigned r; asm volatile("v_cvt_pk_bf16_f32 %0, %1, %2" : "=v"(r) : "v"(lo), "v"(hi)); return r; }
; __device__ __forceinline__ float wave_sum(float v) {
; #pragma unroll
;     for (int o = 1; o < 64; o <<= 1) v += __shfl_xor(v, o);
;     return v;
; }
; __device__ __forceinline__ void rms_row(const f32x4 (&v)[4], const float* g, int lane, float& rs, f32x4 (&y)[4]) {
;     ...
;     rs = __builtin_amdgcn_rsqf(wave_sum(s) * (1.f / DM) + EPS);
; #pragma unroll
;     for (int j = 0; j < 4; ++j) { const f32x4 gv = *((const f32x4*)g + lane + 64 * j); y[j] = v[j] * rs * gv; }
; }
; __device__ __forceinline__ void load_bf16_row(const bf16* row, int lane, f32x4 (&v)[4]) {
;     const u32x2* p = (const u32x2*)row + lane;
; #pragma unroll
;     for (int j = 0; j < 4; ++j) { const u32x2 w = p[64 * j]; v[j] = (f32x4){bflo(w.x), bfhi(w.x), bflo(w.y), bfhi(w.y)}; }
; }
; __device__ __forceinline__ void store_bf16_row(bf16* orow, int lane, const f32x4 (&y)[4]) {
;     u32x2* o8 = (u32x2*)orow + lane;
; #pragma unroll
;     for (int j = 0; j < 4; ++j) { u32x2 w; w.x = cvt_pk_bf16(y[j].x, y[j].y); w.y = cvt_pk_bf16(y[j].z, y[j].w); o8[64 * j] = w; }
; }
	v_add_f32_e32 v212, v212, v210
	v_add_f32_e32 v216, v216, v214
	v_add_f32_e32 v220, v220, v218
	v_add_f32_e32 v224, v224, v222
	ds_bpermute_b32 v210, v181, v212
	ds_bpermute_b32 v214, v181, v216
	ds_bpermute_b32 v218, v181, v220
	ds_bpermute_b32 v222, v181, v224
	s_waitcnt lgkmcnt(0)
	v_add_f32_e32 v212, v212, v210
	v_add_f32_e32 v216, v216, v214
	v_add_f32_e32 v220, v220, v218
	v_add_f32_e32 v224, v224, v222
	v_fmamk_f32 v212, v212, 0x3a800000, v207
	v_fmamk_f32 v216, v216, 0x3a800000, v207
	v_fmamk_f32 v220, v220, 0x3a800000, v207
	v_fmamk_f32 v224, v224, 0x3a800000, v207
	v_rsq_f32_e32 v212, v212
	v_rsq_f32_e32 v216, v216
	v_rsq_f32_e32 v220, v220
	v_rsq_f32_e32 v224, v224
	s_nop 1
	v_lshlrev_b32_e32 v210, 16, v48
	v_and_b32_e32 v211, 0xffff0000, v48
	v_mul_f32_e32 v210, v210, v212
	v_mul_f32_e32 v211, v211, v212
	v_mul_f32_e32 v210, v210, v0
	v_mul_f32_e32 v211, v211, v1
	v_cvt_pk_bf16_f32 v48, v210, v211
	v_lshlrev_b32_e32 v210, 16, v49
	v_and_b32_e32 v211, 0xffff0000, v49
	v_mul_f32_e32 v210, v210, v212
	v_mul_f32_e32 v211, v211, v212
	v_mul_f32_e32 v210, v210, v2
	v_mul_f32_e32 v211, v211, v3
	v_cvt_pk_bf16_f32 v49, v210, v211
	v_lshlrev_b32_e32 v210, 16, v50
	v_and_b32_e32 v211, 0xffff0000, v50
	v_mul_f32_e32 v210, v210, v212
	v_mul_f32_e32 v211, v211, v212
	v_mul_f32_e32 v210, v210, v4
	v_mul_f32_e32 v211, v211, v5
	v_cvt_pk_bf16_f32 v50, v210, v211
	v_lshlrev_b32_e32 v210, 16, v51
	v_and_b32_e32 v211, 0xffff0000, v51
	v_mul_f32_e32 v210, v210, v212
	v_mul_f32_e32 v211, v211, v212
	v_mul_f32_e32 v210, v210, v6
	v_mul_f32_e32 v211, v211, v7
	v_cvt_pk_bf16_f32 v51, v210, v211
	v_lshlrev_b32_e32 v210, 16, v52
	v_and_b32_e32 v211, 0xffff0000, v52
	v_mul_f32_e32 v210, v210, v212
	v_mul_f32_e32 v211, v211, v212
	v_mul_f32_e32 v210, v210, v8
	v_mul_f32_e32 v211, v211, v9
	v_cvt_pk_bf16_f32 v52, v210, v211
	v_lshlrev_b32_e32 v210, 16, v53
	v_and_b32_e32 v211, 0xffff0000, v53
	v_mul_f32_e32 v210, v210, v212
	v_mul_f32_e32 v211, v211, v212
	v_mul_f32_e32 v210, v210, v10
	v_mul_f32_e32 v211, v211, v11
	v_cvt_pk_bf16_f32 v53, v210, v211
	v_lshlrev_b32_e32 v210, 16, v54
	v_and_b32_e32 v211, 0xffff0000, v54
	v_mul_f32_e32 v210, v210, v212
	v_mul_f32_e32 v211, v211, v212
	v_mul_f32_e32 v210, v210, v12
	v_mul_f32_e32 v211, v211, v13
	v_cvt_pk_bf16_f32 v54, v210, v211
	v_lshlrev_b32_e32 v210, 16, v55
	v_and_b32_e32 v211, 0xffff0000, v55
	v_mul_f32_e32 v210, v210, v212
	v_mul_f32_e32 v211, v211, v212
	v_mul_f32_e32 v210, v210, v14
	v_mul_f32_e32 v211, v211, v15
	v_cvt_pk_bf16_f32 v55, v210, v211
	s_add_u32 s72, s78, 0x2000
	s_addc_u32 s73, s79, 0
	global_store_dwordx4 v184, v[48:51], s[72:73]
	global_store_dwordx4 v184, v[52:55], s[72:73] offset:1024
	v_lshlrev_b32_e32 v214, 16, v56
	v_and_b32_e32 v215, 0xffff0000, v56
	v_mul_f32_e32 v214, v214, v216
	v_mul_f32_e32 v215, v215, v216
	v_mul_f32_e32 v214, v214, v0
	v_mul_f32_e32 v215, v215, v1
	v_cvt_pk_bf16_f32 v56, v214, v215
	v_lshlrev_b32_e32 v214, 16, v57
	v_and_b32_e32 v215, 0xffff0000, v57
	v_mul_f32_e32 v214, v214, v216
	v_mul_f32_e32 v215, v215, v216
	v_mul_f32_e32 v214, v214, v2
	v_mul_f32_e32 v215, v215, v3
	v_cvt_pk_bf16_f32 v57, v214, v215
	v_lshlrev_b32_e32 v214, 16, v58
	v_and_b32_e32 v215, 0xffff0000, v58
	v_mul_f32_e32 v214, v214, v216
	v_mul_f32_e32 v215, v215, v216
	v_mul_f32_e32 v214, v214, v4
	v_mul_f32_e32 v215, v215, v5
	v_cvt_pk_bf16_f32 v58, v214, v215
	v_lshlrev_b32_e32 v214, 16, v59
	v_and_b32_e32 v215, 0xffff0000, v59
	v_mul_f32_e32 v214, v214, v216
	v_mul_f32_e32 v215, v215, v216
	v_mul_f32_e32 v214, v214, v6
	v_mul_f32_e32 v215, v215, v7
	v_cvt_pk_bf16_f32 v59, v214, v215
	v_lshlrev_b32_e32 v214, 16, v60
	v_and_b32_e32 v215, 0xffff0000, v60
	v_mul_f32_e32 v214, v214, v216
	v_mul_f32_e32 v215, v215, v216
	v_mul_f32_e32 v214, v214, v8
	v_mul_f32_e32 v215, v215, v9
	v_cvt_pk_bf16_f32 v60, v214, v215
	v_lshlrev_b32_e32 v214, 16, v61
	v_and_b32_e32 v215, 0xffff0000, v61
	v_mul_f32_e32 v214, v214, v216
	v_mul_f32_e32 v215, v215, v216
	v_mul_f32_e32 v214, v214, v10
	v_mul_f32_e32 v215, v215, v11
	v_cvt_pk_bf16_f32 v61, v214, v215
	v_lshlrev_b32_e32 v214, 16, v62
	v_and_b32_e32 v215, 0xffff0000, v62
	v_mul_f32_e32 v214, v214, v216
	v_mul_f32_e32 v215, v215, v216
	v_mul_f32_e32 v214, v214, v12
	v_mul_f32_e32 v215, v215, v13
	v_cvt_pk_bf16_f32 v62, v214, v215
	v_lshlrev_b32_e32 v214, 16, v63
	v_and_b32_e32 v215, 0xffff0000, v63
	v_mul_f32_e32 v214, v214, v216
	v_mul_f32_e32 v215, v215, v216
; __device__ __forceinline__ unsigned cvt_pk_bf16(float lo, float hi) { unsigned r; asm volatile("v_cvt_pk_bf16_f32 %0, %1, %2" : "=v"(r) : "v"(lo), "v"(hi)); return r; }
; __device__ __forceinline__ void rms_row(const f32x4 (&v)[4], const float* g, int lane, float& rs, f32x4 (&y)[4]) {
;     ...
;     for (int j = 0; j < 4; ++j) { const f32x4 gv = *((const f32x4*)g + lane + 64 * j); y[j] = v[j] * rs * gv; }
; }
; __device__ __forceinline__ void load_bf16_row(const bf16* row, int lane, f32x4 (&v)[4]) {
;     const u32x2* p = (const u32x2*)row + lane;
; #pragma unroll
;     for (int j = 0; j < 4; ++j) { const u32x2 w = p[64 * j]; v[j] = (f32x4){bflo(w.x), bfhi(w.x), bflo(w.y), bfhi(w.y)}; }
; }
; __device__ __forceinline__ void store_bf16_row(bf16* orow, int lane, const f32x4 (&y)[4]) {
;     u32x2* o8 = (u32x2*)orow + lane;
; #pragma unroll
;     for (int j = 0; j < 4; ++j) { u32x2 w; w.x = cvt_pk_bf16(y[j].x, y[j].y); w.y = cvt_pk_bf16(y[j].z, y[j].w); o8[64 * j] = w; }
; }
	v_mul_f32_e32 v214, v214, v14
	v_mul_f32_e32 v215, v215, v15
	v_cvt_pk_bf16_f32 v63, v214, v215
	s_add_u32 s72, s78, 0x2800
	s_addc_u32 s73, s79, 0
	global_store_dwordx4 v184, v[56:59], s[72:73]
	global_store_dwordx4 v184, v[60:63], s[72:73] offset:1024
	v_lshlrev_b32_e32 v218, 16, v64
	v_and_b32_e32 v219, 0xffff0000, v64
	v_mul_f32_e32 v218, v218, v220
	v_mul_f32_e32 v219, v219, v220
	v_mul_f32_e32 v218, v218, v0
	v_mul_f32_e32 v219, v219, v1
	v_cvt_pk_bf16_f32 v64, v218, v219
	v_lshlrev_b32_e32 v218, 16, v65
	v_and_b32_e32 v219, 0xffff0000, v65
	v_mul_f32_e32 v218, v218, v220
	v_mul_f32_e32 v219, v219, v220
	v_mul_f32_e32 v218, v218, v2
	v_mul_f32_e32 v219, v219, v3
	v_cvt_pk_bf16_f32 v65, v218, v219
	v_lshlrev_b32_e32 v218, 16, v66
	v_and_b32_e32 v219, 0xffff0000, v66
	v_mul_f32_e32 v218, v218, v220
	v_mul_f32_e32 v219, v219, v220
	v_mul_f32_e32 v218, v218, v4
	v_mul_f32_e32 v219, v219, v5
	v_cvt_pk_bf16_f32 v66, v218, v219
	v_lshlrev_b32_e32 v218, 16, v67
	v_and_b32_e32 v219, 0xffff0000, v67
	v_mul_f32_e32 v218, v218, v220
	v_mul_f32_e32 v219, v219, v220
	v_mul_f32_e32 v218, v218, v6
	v_mul_f32_e32 v219, v219, v7
	v_cvt_pk_bf16_f32 v67, v218, v219
	v_lshlrev_b32_e32 v218, 16, v68
	v_and_b32_e32 v219, 0xffff0000, v68
	v_mul_f32_e32 v218, v218, v220
	v_mul_f32_e32 v219, v219, v220
	v_mul_f32_e32 v218, v218, v8
	v_mul_f32_e32 v219, v219, v9
	v_cvt_pk_bf16_f32 v68, v218, v219
	v_lshlrev_b32_e32 v218, 16, v69
	v_and_b32_e32 v219, 0xffff0000, v69
	v_mul_f32_e32 v218, v218, v220
	v_mul_f32_e32 v219, v219, v220
	v_mul_f32_e32 v218, v218, v10
	v_mul_f32_e32 v219, v219, v11
	v_cvt_pk_bf16_f32 v69, v218, v219
	v_lshlrev_b32_e32 v218, 16, v70
	v_and_b32_e32 v219, 0xffff0000, v70
	v_mul_f32_e32 v218, v218, v220
	v_mul_f32_e32 v219, v219, v220
	v_mul_f32_e32 v218, v218, v12
	v_mul_f32_e32 v219, v219, v13
	v_cvt_pk_bf16_f32 v70, v218, v219
	v_lshlrev_b32_e32 v218, 16, v71
	v_and_b32_e32 v219, 0xffff0000, v71
	v_mul_f32_e32 v218, v218, v220
	v_mul_f32_e32 v219, v219, v220
	v_mul_f32_e32 v218, v218, v14
	v_mul_f32_e32 v219, v219, v15
	v_cvt_pk_bf16_f32 v71, v218, v219
	s_add_u32 s72, s78, 0x3000
	s_addc_u32 s73, s79, 0
	global_store_dwordx4 v184, v[64:67], s[72:73]
	global_store_dwordx4 v184, v[68:71], s[72:73] offset:1024
	v_lshlrev_b32_e32 v222, 16, v72
	v_and_b32_e32 v223, 0xffff0000, v72
	v_mul_f32_e32 v222, v222, v224
	v_mul_f32_e32 v223, v223, v224
	v_mul_f32_e32 v222, v222, v0
	v_mul_f32_e32 v223, v223, v1
	v_cvt_pk_bf16_f32 v72, v222, v223
	v_lshlrev_b32_e32 v222, 16, v73
	v_and_b32_e32 v223, 0xffff0000, v73
	v_mul_f32_e32 v222, v222, v224
	v_mul_f32_e32 v223, v223, v224
	v_mul_f32_e32 v222, v222, v2
	v_mul_f32_e32 v223, v223, v3
	v_cvt_pk_bf16_f32 v73, v222, v223
	v_lshlrev_b32_e32 v222, 16, v74
	v_and_b32_e32 v223, 0xffff0000, v74
	v_mul_f32_e32 v222, v222, v224
	v_mul_f32_e32 v223, v223, v224
	v_mul_f32_e32 v222, v222, v4
	v_mul_f32_e32 v223, v223, v5
	v_cvt_pk_bf16_f32 v74, v222, v223
	v_lshlrev_b32_e32 v222, 16, v75
	v_and_b32_e32 v223, 0xffff0000, v75
	v_mul_f32_e32 v222, v222, v224
	v_mul_f32_e32 v223, v223, v224
	v_mul_f32_e32 v222, v222, v6
	v_mul_f32_e32 v223, v223, v7
	v_cvt_pk_bf16_f32 v75, v222, v223
	v_lshlrev_b32_e32 v222, 16, v76
	v_and_b32_e32 v223, 0xffff0000, v76
	v_mul_f32_e32 v222, v222, v224
	v_mul_f32_e32 v223, v223, v224
	v_mul_f32_e32 v222, v222, v8
	v_mul_f32_e32 v223, v223, v9
	v_cvt_pk_bf16_f32 v76, v222, v223
	v_lshlrev_b32_e32 v222, 16, v77
	v_and_b32_e32 v223, 0xffff0000, v77
	v_mul_f32_e32 v222, v222, v224
	v_mul_f32_e32 v223, v223, v224
	v_mul_f32_e32 v222, v222, v10
	v_mul_f32_e32 v223, v223, v11
	v_cvt_pk_bf16_f32 v77, v222, v223
	v_lshlrev_b32_e32 v222, 16, v78
	v_and_b32_e32 v223, 0xffff0000, v78
	v_mul_f32_e32 v222, v222, v224
	v_mul_f32_e32 v223, v223, v224
	v_mul_f32_e32 v222, v222, v12
	v_mul_f32_e32 v223, v223, v13
	v_cvt_pk_bf16_f32 v78, v222, v223
	v_lshlrev_b32_e32 v222, 16, v79
	v_and_b32_e32 v223, 0xffff0000, v79
	v_mul_f32_e32 v222, v222, v224
	v_mul_f32_e32 v223, v223, v224
	v_mul_f32_e32 v222, v222, v14
	v_mul_f32_e32 v223, v223, v15
	v_cvt_pk_bf16_f32 v79, v222, v223
	s_add_u32 s72, s78, 0x3800
	s_addc_u32 s73, s79, 0
	global_store_dwordx4 v184, v[72:75], s[72:73]
	global_store_dwordx4 v184, v[76:79], s[72:73] offset:1024
	s_add_u32 s76, s76, 0x4000
	s_addc_u32 s77, s77, 0
	s_add_u32 s78, s78, 0x4000
	s_addc_u32 s79, s79, 0
	s_sub_u32 s80, s80, 1
	s_cmp_lg_u32 s80, 0
	s_cbranch_scc1 .Lf4_batch

; template <int NSLICE> __device__ __forceinline__ void rms_phase(ArgP a, const float* g, bool final_out, int G) {
;     ...
;     for (int t = (NGW - 1 - gw); t < M_REAL - R_META; t += NGW) {
;         const int m = R_META + t;
;         if (final_out && m < R_SAMP) continue;
;         f32x4 v[4]; load_bf16_row(H + (size_t)m * DM, lane, v);
;         const bf16* PART = (const bf16*)(a->ws + WS_P + 6 * ROWBUF) + (size_t)t * DM;
; #pragma unroll
;         for (int sl = 0; sl < NSLICE; ++sl) {
;             f32x4 pv[4]; load_bf16_row(PART + (size_t)sl * (MP - R_META) * DM, lane, pv);
; #pragma unroll
;             for (int j = 0; j < 4; ++j) v[j] = v[j] + pv[j];
;         }
;         if (!final_out) store_bf16_row(H + (size_t)m * DM, lane, v);
;         float rs; f32x4 y[4]; rms_row(v, g, lane, rs, y);
.LBB0_1053:
	s_or_b64 exec, exec, s[34:35]
	v_readlane_b32 s2, v254, 4
	v_readlane_b32 s3, v254, 5
	s_mov_b64 s[0:1], s[2:3]
	s_waitcnt lgkmcnt(0)
	s_barrier
	v_readlane_b32 s0, v255, 54
	s_nop 1
	s_cmp_eq_u32 s0, 0
	s_cbranch_scc1 .Lp5_full
	v_readlane_b32 s0, v254, 4
	v_readlane_b32 s1, v254, 5
	s_nop 1
	s_load_dwordx2 s[2:3], s[0:1], 0x80
	s_load_dwordx2 s[6:7], s[0:1], 0x58
	v_readlane_b32 s8, v255, 6
	s_nop 1
	s_lshl_b32 s8, s8, 12
	v_lshrrev_b32_e32 v183, 6, v193
	v_and_b32_e32 v182, 63, v193
	v_readlane_b32 s10, v254, 9
	v_readfirstlane_b32 s9, v183
	s_nop 1
	s_add_u32 s9, s9, s10
	s_sub_u32 s10, 0x7ff, s9
	s_lshl_b32 s11, s9, 11
	v_lshlrev_b32_e32 v183, 4, v182
	v_add_u32_e32 v184, s11, v183
	s_lshl_b32 s11, s10, 11
	v_add_u32_e32 v185, s11, v183
	v_lshlrev_b32_e32 v186, 5, v182
	v_xor_b32_e32 v176, 1, v182
	v_lshlrev_b32_e32 v176, 2, v176
	v_xor_b32_e32 v177, 2, v182
	v_lshlrev_b32_e32 v177, 2, v177
	v_xor_b32_e32 v178, 4, v182
	v_lshlrev_b32_e32 v178, 2, v178
	v_xor_b32_e32 v179, 8, v182
	v_lshlrev_b32_e32 v179, 2, v179
	v_xor_b32_e32 v180, 16, v182
	v_lshlrev_b32_e32 v180, 2, v180
	v_xor_b32_e32 v181, 32, v182
	v_lshlrev_b32_e32 v181, 2, v181
	s_waitcnt lgkmcnt(0)
	s_add_u32 s6, s6, s8
	s_addc_u32 s7, s7, 0
	s_cmp_lt_u32 s10, 0x480
	s_cbranch_scc0 .Lp5l_noleft_ld
	s_add_u32 s12, s2, 0x9580000
	s_addc_u32 s13, s3, 0
	global_load_dwordx4 v[80:83], v185, s[12:13]
	global_load_dwordx4 v[84:87], v185, s[12:13] offset:1024
	s_add_u32 s12, s2, 0x18980000
	s_addc_u32 s13, s3, 0
	global_load_dwordx4 v[88:91], v185, s[12:13]
	global_load_dwordx4 v[92:95], v185, s[12:13] offset:1024
	s_add_u32 s12, s2, 0x18c00000
	s_addc_u32 s13, s3, 0
	global_load_dwordx4 v[96:99], v185, s[12:13]
	global_load_dwordx4 v[100:103], v185, s[12:13] offset:1024
	s_add_u32 s12, s2, 0x18e80000
	s_addc_u32 s13, s3, 0
	global_load_dwordx4 v[104:107], v185, s[12:13]
	global_load_dwordx4 v[108:111], v185, s[12:13] offset:1024
	s_add_u32 s12, s2, 0x19100000
	s_addc_u32 s13, s3, 0
	global_load_dwordx4 v[112:115], v185, s[12:13]
	global_load_dwordx4 v[116:119], v185, s[12:13] offset:1024
.Lp5l_noleft_ld:
	global_load_dwordx4 v[0:3], v186, s[6:7]
	global_load_dwordx4 v[4:7], v186, s[6:7] offset:16
	global_load_dwordx4 v[8:11], v186, s[6:7] offset:2048
	global_load_dwordx4 v[12:15], v186, s[6:7] offset:2064
	s_waitcnt vmcnt(0)
	s_cmp_lt_u32 s10, 0x480
	s_cbranch_scc0 .Lp5l_done
	v_lshlrev_b32_e32 v226, 16, v80
	v_and_b32_e32 v227, 0xffff0000, v80
	v_lshlrev_b32_e32 v228, 16, v81
	v_and_b32_e32 v229, 0xffff0000, v81
	v_lshlrev_b32_e32 v230, 16, v82
	v_and_b32_e32 v231, 0xffff0000, v82
	v_lshlrev_b32_e32 v232, 16, v83
	v_and_b32_e32 v233, 0xffff0000, v83
	v_lshlrev_b32_e32 v234, 16, v84
	v_and_b32_e32 v235, 0xffff0000, v84
	v_lshlrev_b32_e32 v236, 16, v85
	v_and_b32_e32 v237, 0xffff0000, v85
	v_lshlrev_b32_e32 v238, 16, v86
	v_and_b32_e32 v239, 0xffff0000, v86
	v_lshlrev_b32_e32 v240, 16, v87
	v_and_b32_e32 v241, 0xffff0000, v87
	v_lshlrev_b32_e32 v242, 16, v88
	v_and_b32_e32 v243, 0xffff0000, v88
	v_add_f32_e32 v226, v226, v242
	v_add_f32_e32 v227, v227, v243
	v_lshlrev_b32_e32 v242, 16, v89
	v_and_b32_e32 v243, 0xffff0000, v89
	v_add_f32_e32 v228, v228, v242
	v_add_f32_e32 v229, v229, v243
	v_lshlrev_b32_e32 v242, 16, v90
	v_and_b32_e32 v243, 0xffff0000, v90
	v_add_f32_e32 v230, v230, v242
	v_add_f32_e32 v231, v231, v243
	v_lshlrev_b32_e32 v242, 16, v91
	v_and_b32_e32 v243, 0xffff0000, v91
	v_add_f32_e32 v232, v232, v242
	v_add_f32_e32 v233, v233, v243
	v_lshlrev_b32_e32 v242, 16, v92
	v_and_b32_e32 v243, 0xffff0000, v92
	v_add_f32_e32 v234, v234, v242
	v_add_f32_e32 v235, v235, v243
	v_lshlrev_b32_e32 v242, 16, v93
	v_and_b32_e32 v243, 0xffff0000, v93
	v_add_f32_e32 v236, v236, v242
	v_add_f32_e32 v237, v237, v243
	v_lshlrev_b32_e32 v242, 16, v94
	v_and_b32_e32 v243, 0xffff0000, v94
	v_add_f32_e32 v238, v238, v242
	v_add_f32_e32 v239, v239, v243
	v_lshlrev_b32_e32 v242, 16, v95
	v_and_b32_e32 v243, 0xffff0000, v95
	v_add_f32_e32 v240, v240, v242
	v_add_f32_e32 v241, v241, v243
	v_lshlrev_b32_e32 v242, 16, v96
	v_and_b32_e32 v243, 0xffff0000, v96
	v_add_f32_e32 v226, v226, v242
	v_add_f32_e32 v227, v227, v243
	v_lshlrev_b32_e32 v242, 16, v97
	v_and_b32_e32 v243, 0xffff0000, v97
	v_add_f32_e32 v228, v228, v242
	v_add_f32_e32 v229, v229, v243
	v_lshlrev_b32_e32 v242, 16, v98
	v_and_b32_e32 v243, 0xffff0000, v98
	v_add_f32_e32 v230, v230, v242
	v_add_f32_e32 v231, v231, v243
	v_lshlrev_b32_e32 v242, 16, v99
	v_and_b32_e32 v243, 0xffff0000, v99
	v_add_f32_e32 v232, v232, v242
	v_add_f32_e32 v233, v233, v243
	v_lshlrev_b32_e32 v242, 16, v100
	v_and_b32_e32 v243, 0xffff0000, v100
	v_add_f32_e32 v234, v234, v242
	v_add_f32_e32 v235, v235, v243
	v_lshlrev_b32_e32 v242, 16, v101
	v_and_b32_e32 v243, 0xffff0000, v101
	v_add_f32_e32 v236, v236, v242
	v_add_f32_e32 v237, v237, v243
	v_lshlrev_b32_e32 v242, 16, v102
	v_and_b32_e32 v243, 0xffff0000, v102
	v_add_f32_e32 v238, v238, v242
	v_add_f32_e32 v239, v239, v243
	v_lshlrev_b32_e32 v242, 16, v103
	v_and_b32_e32 v243, 0xffff0000, v103
	v_add_f32_e32 v240, v240, v242
	v_add_f32_e32 v241, v241, v243
	v_lshlrev_b32_e32 v242, 16, v104
	v_and_b32_e32 v243, 0xffff0000, v104
; template <int NSLICE> __device__ __forceinline__ void rms_phase(ArgP a, const float* g, bool final_out, int G) {
;     ...
;         for (int sl = 0; sl < NSLICE; ++sl) {
;             f32x4 pv[4]; load_bf16_row(PART + (size_t)sl * (MP - R_META) * DM, lane, pv);
; #pragma unroll
;             for (int j = 0; j < 4; ++j) v[j] = v[j] + pv[j];
;         }
;         if (!final_out) store_bf16_row(H + (size_t)m * DM, lane, v);
;         float rs; f32x4 y[4]; rms_row(v, g, lane, rs, y);
;         if (!final_out) store_bf16_row(XN + (size_t)m * DM, lane, y);
	v_add_f32_e32 v226, v226, v242
	v_add_f32_e32 v227, v227, v243
	v_lshlrev_b32_e32 v242, 16, v105
	v_and_b32_e32 v243, 0xffff0000, v105
	v_add_f32_e32 v228, v228, v242
	v_add_f32_e32 v229, v229, v243
	v_lshlrev_b32_e32 v242, 16, v106
	v_and_b32_e32 v243, 0xffff0000, v106
	v_add_f32_e32 v230, v230, v242
	v_add_f32_e32 v231, v231, v243
	v_lshlrev_b32_e32 v242, 16, v107
	v_and_b32_e32 v243, 0xffff0000, v107
	v_add_f32_e32 v232, v232, v242
	v_add_f32_e32 v233, v233, v243
	v_lshlrev_b32_e32 v242, 16, v108
	v_and_b32_e32 v243, 0xffff0000, v108
	v_add_f32_e32 v234, v234, v242
	v_add_f32_e32 v235, v235, v243
	v_lshlrev_b32_e32 v242, 16, v109
	v_and_b32_e32 v243, 0xffff0000, v109
	v_add_f32_e32 v236, v236, v242
	v_add_f32_e32 v237, v237, v243
	v_lshlrev_b32_e32 v242, 16, v110
	v_and_b32_e32 v243, 0xffff0000, v110
	v_add_f32_e32 v238, v238, v242
	v_add_f32_e32 v239, v239, v243
	v_lshlrev_b32_e32 v242, 16, v111
	v_and_b32_e32 v243, 0xffff0000, v111
	v_add_f32_e32 v240, v240, v242
	v_add_f32_e32 v241, v241, v243
	v_lshlrev_b32_e32 v242, 16, v112
	v_and_b32_e32 v243, 0xffff0000, v112
	v_add_f32_e32 v226, v226, v242
	v_add_f32_e32 v227, v227, v243
	v_lshlrev_b32_e32 v242, 16, v113
	v_and_b32_e32 v243, 0xffff0000, v113
	v_add_f32_e32 v228, v228, v242
	v_add_f32_e32 v229, v229, v243
	v_lshlrev_b32_e32 v242, 16, v114
	v_and_b32_e32 v243, 0xffff0000, v114
	v_add_f32_e32 v230, v230, v242
	v_add_f32_e32 v231, v231, v243
	v_lshlrev_b32_e32 v242, 16, v115
	v_and_b32_e32 v243, 0xffff0000, v115
	v_add_f32_e32 v232, v232, v242
	v_add_f32_e32 v233, v233, v243
	v_lshlrev_b32_e32 v242, 16, v116
	v_and_b32_e32 v243, 0xffff0000, v116
	v_add_f32_e32 v234, v234, v242
	v_add_f32_e32 v235, v235, v243
	v_lshlrev_b32_e32 v242, 16, v117
	v_and_b32_e32 v243, 0xffff0000, v117
	v_add_f32_e32 v236, v236, v242
	v_add_f32_e32 v237, v237, v243
	v_lshlrev_b32_e32 v242, 16, v118
	v_and_b32_e32 v243, 0xffff0000, v118
	v_add_f32_e32 v238, v238, v242
	v_add_f32_e32 v239, v239, v243
	v_lshlrev_b32_e32 v242, 16, v119
	v_and_b32_e32 v243, 0xffff0000, v119
	v_add_f32_e32 v240, v240, v242
	v_add_f32_e32 v241, v241, v243
	v_cvt_pk_bf16_f32 v80, v226, v227
	v_cvt_pk_bf16_f32 v81, v228, v229
	v_cvt_pk_bf16_f32 v82, v230, v231
	v_cvt_pk_bf16_f32 v83, v232, v233
	v_cvt_pk_bf16_f32 v84, v234, v235
	v_cvt_pk_bf16_f32 v85, v236, v237
	v_cvt_pk_bf16_f32 v86, v238, v239
	v_cvt_pk_bf16_f32 v87, v240, v241
	s_add_u32 s12, s2, 0x9580000
	s_addc_u32 s13, s3, 0
	global_store_dwordx4 v185, v[80:83], s[12:13]
	global_store_dwordx4 v185, v[84:87], s[12:13] offset:1024
	v_mul_f32_e32 v244, v226, v226
	v_mul_f32_e32 v245, v227, v227
	v_fmac_f32_e32 v244, v228, v228
	v_fmac_f32_e32 v245, v229, v229
	v_fmac_f32_e32 v244, v230, v230
	v_fmac_f32_e32 v245, v231, v231
	v_fmac_f32_e32 v244, v232, v232
	v_fmac_f32_e32 v245, v233, v233
	v_fmac_f32_e32 v244, v234, v234
	v_fmac_f32_e32 v245, v235, v235
	v_fmac_f32_e32 v244, v236, v236
	v_fmac_f32_e32 v245, v237, v237
	v_fmac_f32_e32 v244, v238, v238
	v_fmac_f32_e32 v245, v239, v239
	v_fmac_f32_e32 v244, v240, v240
	v_fmac_f32_e32 v245, v241, v241
	v_add_f32_e32 v244, v244, v245
	ds_bpermute_b32 v242, v176, v244
	s_waitcnt lgkmcnt(0)
	v_add_f32_e32 v244, v244, v242
	ds_bpermute_b32 v242, v177, v244
	s_waitcnt lgkmcnt(0)
	v_add_f32_e32 v244, v244, v242
	ds_bpermute_b32 v242, v178, v244
	s_waitcnt lgkmcnt(0)
	v_add_f32_e32 v244, v244, v242
	ds_bpermute_b32 v242, v179, v244
	s_waitcnt lgkmcnt(0)
	v_add_f32_e32 v244, v244, v242
	ds_bpermute_b32 v242, v180, v244
	s_waitcnt lgkmcnt(0)
	v_add_f32_e32 v244, v244, v242
	ds_bpermute_b32 v242, v181, v244
	s_waitcnt lgkmcnt(0)
	v_add_f32_e32 v244, v244, v242
	v_fmamk_f32 v244, v244, 0x3a800000, v207
	v_rsq_f32_e32 v244, v244
	s_nop 1
	v_mul_f32_e32 v226, v226, v244
	v_mul_f32_e32 v227, v227, v244
	v_mul_f32_e32 v226, v226, v0
	v_mul_f32_e32 v227, v227, v1
	v_cvt_pk_bf16_f32 v88, v226, v227
	v_mul_f32_e32 v228, v228, v244
	v_mul_f32_e32 v229, v229, v244
	v_mul_f32_e32 v228, v228, v2
	v_mul_f32_e32 v229, v229, v3
	v_cvt_pk_bf16_f32 v89, v228, v229
	v_mul_f32_e32 v230, v230, v244
	v_mul_f32_e32 v231, v231, v244
	v_mul_f32_e32 v230, v230, v4
	v_mul_f32_e32 v231, v231, v5
	v_cvt_pk_bf16_f32 v90, v230, v231
	v_mul_f32_e32 v232, v232, v244
	v_mul_f32_e32 v233, v233, v244
	v_mul_f32_e32 v232, v232, v6
	v_mul_f32_e32 v233, v233, v7
	v_cvt_pk_bf16_f32 v91, v232, v233
	v_mul_f32_e32 v234, v234, v244
	v_mul_f32_e32 v235, v235, v244
	v_mul_f32_e32 v234, v234, v8
	v_mul_f32_e32 v235, v235, v9
	v_cvt_pk_bf16_f32 v92, v234, v235
	v_mul_f32_e32 v236, v236, v244
	v_mul_f32_e32 v237, v237, v244
	v_mul_f32_e32 v236, v236, v10
	v_mul_f32_e32 v237, v237, v11
	v_cvt_pk_bf16_f32 v93, v236, v237
	v_mul_f32_e32 v238, v238, v244
	v_mul_f32_e32 v239, v239, v244
	v_mul_f32_e32 v238, v238, v12
	v_mul_f32_e32 v239, v239, v13
	v_cvt_pk_bf16_f32 v94, v238, v239
	v_mul_f32_e32 v240, v240, v244
	v_mul_f32_e32 v241, v241, v244
	v_mul_f32_e32 v240, v240, v14
	v_mul_f32_e32 v241, v241, v15
	v_cvt_pk_bf16_f32 v95, v240, v241
	s_add_u32 s12, s2, 0x7300000
	s_addc_u32 s13, s3, 0
	global_store_dwordx4 v185, v[88:91], s[12:13]
	global_store_dwordx4 v185, v[92:95], s[12:13] offset:1024

; template <int NSLICE> __device__ __forceinline__ void rms_phase(ArgP a, const float* g, bool final_out, int G) {
;     int tid_ = threadIdx.x; asm volatile("" : "+v"(tid_));
;     const int tid = tid_, lane = tid & 63, wave = tid >> 6;
;     const int gw = blockIdx.x * NWAVES + wave, NGW = G * NWAVES;
;     bf16* H = (bf16*)(a->ws + WS_H); bf16* XN = (bf16*)(a->ws + WS_XN);
;     for (int m = gw; m < R_META; m += 2 * NGW) {
;     ...
;     for (int t = (NGW - 1 - gw); t < M_REAL - R_META; t += NGW) {
;         const int m = R_META + t;
;         if (final_out && m < R_SAMP) continue;
;         f32x4 v[4]; load_bf16_row(H + (size_t)m * DM, lane, v);
;         const bf16* PART = (const bf16*)(a->ws + WS_P + 6 * ROWBUF) + (size_t)t * DM;
; #pragma unroll
;         for (int sl = 0; sl < NSLICE; ++sl) {
;             f32x4 pv[4]; load_bf16_row(PART + (size_t)sl * (MP - R_META) * DM, lane, pv);
.Lp5_full:
	v_readlane_b32 s0, v254, 4
	v_readlane_b32 s1, v254, 5
	s_nop 1
	s_load_dwordx2 s[2:3], s[0:1], 0x80
	s_load_dwordx2 s[6:7], s[0:1], 0x58
	v_readlane_b32 s8, v255, 6
	s_nop 1
	s_lshl_b32 s8, s8, 12
	v_lshrrev_b32_e32 v183, 6, v193
	v_and_b32_e32 v182, 63, v193
	v_readlane_b32 s10, v254, 9
	v_readfirstlane_b32 s9, v183
	s_nop 1
	s_add_u32 s9, s9, s10
	s_sub_u32 s10, 0x7ff, s9
	s_lshl_b32 s11, s9, 11
	v_lshlrev_b32_e32 v183, 4, v182
	v_add_u32_e32 v184, s11, v183
	s_lshl_b32 s11, s10, 11
	v_add_u32_e32 v185, s11, v183
	v_lshlrev_b32_e32 v186, 5, v182
	v_xor_b32_e32 v176, 1, v182
	v_lshlrev_b32_e32 v176, 2, v176
	v_xor_b32_e32 v177, 2, v182
	v_lshlrev_b32_e32 v177, 2, v177
	v_xor_b32_e32 v178, 4, v182
	v_lshlrev_b32_e32 v178, 2, v178
	v_xor_b32_e32 v179, 8, v182
	v_lshlrev_b32_e32 v179, 2, v179
	v_xor_b32_e32 v180, 16, v182
	v_lshlrev_b32_e32 v180, 2, v180
	v_xor_b32_e32 v181, 32, v182
	v_lshlrev_b32_e32 v181, 2, v181
	s_waitcnt lgkmcnt(0)
	s_add_u32 s6, s6, s8
	s_addc_u32 s7, s7, 0
	s_cmp_lt_u32 s10, 0x480
	s_cbranch_scc0 .Lp5f_noleft_ld
	s_add_u32 s12, s2, 0x9580000
	s_addc_u32 s13, s3, 0
	global_load_dwordx4 v[80:83], v185, s[12:13]
	global_load_dwordx4 v[84:87], v185, s[12:13] offset:1024
	s_add_u32 s12, s2, 0x18980000
	s_addc_u32 s13, s3, 0
	global_load_dwordx4 v[88:91], v185, s[12:13]
	global_load_dwordx4 v[92:95], v185, s[12:13] offset:1024
	s_add_u32 s12, s2, 0x18c00000
	s_addc_u32 s13, s3, 0
	global_load_dwordx4 v[96:99], v185, s[12:13]
	global_load_dwordx4 v[100:103], v185, s[12:13] offset:1024
	s_add_u32 s12, s2, 0x18e80000
	s_addc_u32 s13, s3, 0
	global_load_dwordx4 v[104:107], v185, s[12:13]
	global_load_dwordx4 v[108:111], v185, s[12:13] offset:1024
	s_add_u32 s12, s2, 0x19100000
	s_addc_u32 s13, s3, 0
	global_load_dwordx4 v[112:115], v185, s[12:13]
	global_load_dwordx4 v[116:119], v185, s[12:13] offset:1024

; __device__ __forceinline__ void xcd_barrier(const XcdBarrier& b) {
;     asm volatile("s_waitcnt vmcnt(0)" ::: "memory");
;     __syncthreads();
;     if (threadIdx.x == 0) {
;         unsigned* bar = b.bar;
;         __builtin_amdgcn_s_waitcnt(0);
;         unsigned nloc = b.st[0], nx = b.st[1];
;         if (nloc == 0u) { xcd_barrier_complete(bar, b.x, nloc, nx); b.st[0] = nloc; b.st[1] = nx; }
.Lp5f_done:
.Lp5_end:
.LBB0_1061:
	s_movk_i32 s46, 0x47f
	s_or_b64 exec, exec, s[0:1]
	v_readlane_b32 s36, v254, 10
	v_readlane_b32 s33, v254, 12
	v_readlane_b32 s37, v254, 11
	s_waitcnt vmcnt(0)
	s_waitcnt lgkmcnt(0)
	s_barrier
	s_mov_b64 s[34:35], exec
	v_readlane_b32 s0, v254, 13
	v_readlane_b32 s1, v254, 14
	s_and_b64 s[0:1], s[34:35], s[0:1]
	s_mov_b64 exec, s[0:1]
	s_cbranch_execz .LBB0_1105
	v_readlane_b32 s0, v254, 58
	s_waitcnt vmcnt(0) expcnt(0) lgkmcnt(0)
	s_nop 0
	v_mov_b32_e32 v0, s0
	ds_read_b32 v2, v0
	v_readlane_b32 s0, v254, 59
	s_waitcnt lgkmcnt(0)
	v_cmp_ne_u32_e32 vcc, 0, v2
	v_mov_b32_e32 v0, s0
	ds_read_b32 v0, v0
	s_cbranch_vccnz .LBB0_1076
	s_add_u32 s0, s36, 0x1000
	s_addc_u32 s1, s37, 0
	s_add_u32 s2, s36, 0x1100
	s_addc_u32 s3, s37, 0
	s_add_u32 s6, s36, 0x1200
	s_addc_u32 s7, s37, 0
	s_add_u32 s8, s36, 0x1300
	s_addc_u32 s9, s37, 0
	s_mov_b32 s28, 1
	s_mov_b64 s[10:11], 0
	s_branch .LBB0_1066
